# NSA top-k rank loop stops after the causal block range (blocks beyond blk can never outrank a valid one); edit padded to a multiple of 64 bytes
# speedup vs baseline: 1.0126x; 1.0126x over previous
.LBB0_95:
	v_or_b32_e32 v2, s14, v162
	v_bitop3_b32 v3, v2, 63, v180 bitop3:0x48
	v_lshl_add_u32 v3, v3, 2, v0
	ds_read_b32 v3, v3 offset:16384
	v_mov_b32_e32 v4, 0x7149f2ca
	v_readfirstlane_b32 s42, v214
	v_cmp_gt_u32_e32 vcc, v163, v214
	v_mov_b32_e32 v5, 0
	v_sub_u32_e32 v6, 63, v163
	s_waitcnt lgkmcnt(0)
	v_cndmask_b32_e64 v3, v3, v4, s[6:7]
	v_cndmask_b32_e32 v3, v3, v205, vcc
	s_nop 0
	v_mov_b32_e32 v7, v3
	v_readlane_b32 s11, v3, 0
	s_mov_b32 s10, 63
	v_readlane_b32 s13, v3, 1
	s_mov_b32 s12, 62
	v_cmp_gt_i64_e64 s[8:9], s[10:11], v[6:7]
	v_readlane_b32 s11, v3, 2
	s_mov_b32 s10, 61
	v_addc_co_u32_e64 v5, s[8:9], 0, v5, s[8:9]
	v_cmp_gt_i64_e32 vcc, s[12:13], v[6:7]
	v_readlane_b32 s13, v3, 3
	s_mov_b32 s12, 60
	v_addc_co_u32_e32 v5, vcc, 0, v5, vcc
	v_cmp_gt_i64_e64 s[8:9], s[10:11], v[6:7]
	v_readlane_b32 s11, v3, 4
	s_mov_b32 s10, 59
	v_addc_co_u32_e64 v5, s[8:9], 0, v5, s[8:9]
	v_cmp_gt_i64_e32 vcc, s[12:13], v[6:7]
	v_readlane_b32 s13, v3, 5
	s_mov_b32 s12, 58
	v_addc_co_u32_e32 v5, vcc, 0, v5, vcc
	v_cmp_gt_i64_e64 s[8:9], s[10:11], v[6:7]
	v_readlane_b32 s11, v3, 6
	s_mov_b32 s10, 57
	v_addc_co_u32_e64 v5, s[8:9], 0, v5, s[8:9]
	v_cmp_gt_i64_e32 vcc, s[12:13], v[6:7]
	v_readlane_b32 s13, v3, 7
	s_mov_b32 s12, 56
	v_addc_co_u32_e32 v5, vcc, 0, v5, vcc
	v_cmp_gt_i64_e64 s[8:9], s[10:11], v[6:7]
	v_readlane_b32 s11, v3, 8
	s_mov_b32 s10, 55
	v_addc_co_u32_e64 v5, s[8:9], 0, v5, s[8:9]
	v_cmp_gt_i64_e32 vcc, s[12:13], v[6:7]
	v_readlane_b32 s13, v3, 9
	s_mov_b32 s12, 54
	v_addc_co_u32_e32 v5, vcc, 0, v5, vcc
	s_cmp_lt_u32 s42, 8
	s_cbranch_scc1 .Lsel_done
	v_cmp_gt_i64_e64 s[8:9], s[10:11], v[6:7]
	v_readlane_b32 s11, v3, 10
	s_mov_b32 s10, 53
	v_addc_co_u32_e64 v5, s[8:9], 0, v5, s[8:9]
	v_cmp_gt_i64_e32 vcc, s[12:13], v[6:7]
	v_readlane_b32 s13, v3, 11
	s_mov_b32 s12, 52
	v_addc_co_u32_e32 v5, vcc, 0, v5, vcc
	v_cmp_gt_i64_e64 s[8:9], s[10:11], v[6:7]
	v_readlane_b32 s11, v3, 12
	s_mov_b32 s10, 51
	v_addc_co_u32_e64 v5, s[8:9], 0, v5, s[8:9]
	v_cmp_gt_i64_e32 vcc, s[12:13], v[6:7]
	v_readlane_b32 s13, v3, 13
	s_mov_b32 s12, 50
	v_addc_co_u32_e32 v5, vcc, 0, v5, vcc
	v_cmp_gt_i64_e64 s[8:9], s[10:11], v[6:7]
	v_readlane_b32 s11, v3, 14
	s_mov_b32 s10, 49
	v_addc_co_u32_e64 v5, s[8:9], 0, v5, s[8:9]
	v_cmp_gt_i64_e32 vcc, s[12:13], v[6:7]
	v_readlane_b32 s13, v3, 15
	s_mov_b32 s12, 48
	v_addc_co_u32_e32 v5, vcc, 0, v5, vcc
	v_cmp_gt_i64_e64 s[8:9], s[10:11], v[6:7]
	v_readlane_b32 s11, v3, 16
	s_mov_b32 s10, 47
	v_addc_co_u32_e64 v5, s[8:9], 0, v5, s[8:9]
	v_cmp_gt_i64_e32 vcc, s[12:13], v[6:7]
	v_readlane_b32 s13, v3, 17
	s_mov_b32 s12, 46
	v_addc_co_u32_e32 v5, vcc, 0, v5, vcc
	s_cmp_lt_u32 s42, 16
	s_cbranch_scc1 .Lsel_done
	v_cmp_gt_i64_e64 s[8:9], s[10:11], v[6:7]
	v_readlane_b32 s11, v3, 18
	s_mov_b32 s10, 45
	v_addc_co_u32_e64 v5, s[8:9], 0, v5, s[8:9]
	v_cmp_gt_i64_e32 vcc, s[12:13], v[6:7]
	v_readlane_b32 s13, v3, 19
	s_mov_b32 s12, 44
	v_addc_co_u32_e32 v5, vcc, 0, v5, vcc
	v_cmp_gt_i64_e64 s[8:9], s[10:11], v[6:7]
	v_readlane_b32 s11, v3, 20
	s_mov_b32 s10, 43
	v_addc_co_u32_e64 v5, s[8:9], 0, v5, s[8:9]
	v_cmp_gt_i64_e32 vcc, s[12:13], v[6:7]
	v_readlane_b32 s13, v3, 21
	s_mov_b32 s12, 42
	v_addc_co_u32_e32 v5, vcc, 0, v5, vcc
	v_cmp_gt_i64_e64 s[8:9], s[10:11], v[6:7]
	v_readlane_b32 s11, v3, 22
	s_mov_b32 s10, 41
	v_addc_co_u32_e64 v5, s[8:9], 0, v5, s[8:9]
	v_cmp_gt_i64_e32 vcc, s[12:13], v[6:7]
	v_readlane_b32 s13, v3, 23
	s_mov_b32 s12, 40
	v_addc_co_u32_e32 v5, vcc, 0, v5, vcc
	v_cmp_gt_i64_e64 s[8:9], s[10:11], v[6:7]
	v_readlane_b32 s11, v3, 24
	s_mov_b32 s10, 39
	v_addc_co_u32_e64 v5, s[8:9], 0, v5, s[8:9]
	v_cmp_gt_i64_e32 vcc, s[12:13], v[6:7]
	v_readlane_b32 s13, v3, 25
	s_mov_b32 s12, 38
	v_addc_co_u32_e32 v5, vcc, 0, v5, vcc
	s_cmp_lt_u32 s42, 24
	s_cbranch_scc1 .Lsel_done
	v_cmp_gt_i64_e64 s[8:9], s[10:11], v[6:7]
	v_readlane_b32 s11, v3, 26
	s_mov_b32 s10, 37
	v_addc_co_u32_e64 v5, s[8:9], 0, v5, s[8:9]
	v_cmp_gt_i64_e32 vcc, s[12:13], v[6:7]
	v_readlane_b32 s13, v3, 27
	s_mov_b32 s12, 36
	v_addc_co_u32_e32 v5, vcc, 0, v5, vcc
	v_cmp_gt_i64_e64 s[8:9], s[10:11], v[6:7]
	v_readlane_b32 s11, v3, 28
	s_mov_b32 s10, 35
	v_addc_co_u32_e64 v5, s[8:9], 0, v5, s[8:9]
	v_cmp_gt_i64_e32 vcc, s[12:13], v[6:7]
	v_readlane_b32 s13, v3, 29
	s_mov_b32 s12, 34
	v_addc_co_u32_e32 v5, vcc, 0, v5, vcc
	v_cmp_gt_i64_e64 s[8:9], s[10:11], v[6:7]
	v_readlane_b32 s11, v3, 30
	s_mov_b32 s10, 33
	v_addc_co_u32_e64 v5, s[8:9], 0, v5, s[8:9]
	v_cmp_gt_i64_e32 vcc, s[12:13], v[6:7]
	v_readlane_b32 s13, v3, 31
	s_mov_b32 s12, 32
	v_addc_co_u32_e32 v5, vcc, 0, v5, vcc
	v_cmp_gt_i64_e64 s[8:9], s[10:11], v[6:7]
	v_readlane_b32 s11, v3, 32
	s_mov_b32 s10, 31
	v_addc_co_u32_e64 v5, s[8:9], 0, v5, s[8:9]
	v_cmp_gt_i64_e32 vcc, s[12:13], v[6:7]
	v_readlane_b32 s13, v3, 33
	s_mov_b32 s12, 30
	v_addc_co_u32_e32 v5, vcc, 0, v5, vcc
	s_cmp_lt_u32 s42, 32
	s_cbranch_scc1 .Lsel_done
	v_cmp_gt_i64_e64 s[8:9], s[10:11], v[6:7]
	v_readlane_b32 s11, v3, 34
	s_mov_b32 s10, 29
	v_addc_co_u32_e64 v5, s[8:9], 0, v5, s[8:9]
	v_cmp_gt_i64_e32 vcc, s[12:13], v[6:7]
	v_readlane_b32 s13, v3, 35
	s_mov_b32 s12, 28
	v_addc_co_u32_e32 v5, vcc, 0, v5, vcc
	v_cmp_gt_i64_e64 s[8:9], s[10:11], v[6:7]
	v_readlane_b32 s11, v3, 36
	s_mov_b32 s10, 27
	v_addc_co_u32_e64 v5, s[8:9], 0, v5, s[8:9]
	v_cmp_gt_i64_e32 vcc, s[12:13], v[6:7]
	v_readlane_b32 s13, v3, 37
	s_mov_b32 s12, 26
	v_addc_co_u32_e32 v5, vcc, 0, v5, vcc
	v_cmp_gt_i64_e64 s[8:9], s[10:11], v[6:7]
	v_readlane_b32 s11, v3, 38
	s_mov_b32 s10, 25
	v_addc_co_u32_e64 v5, s[8:9], 0, v5, s[8:9]
	v_cmp_gt_i64_e32 vcc, s[12:13], v[6:7]
	v_readlane_b32 s13, v3, 39
	s_mov_b32 s12, 24
	v_addc_co_u32_e32 v5, vcc, 0, v5, vcc
	v_cmp_gt_i64_e64 s[8:9], s[10:11], v[6:7]
	v_readlane_b32 s11, v3, 40
	s_mov_b32 s10, 23
	v_addc_co_u32_e64 v5, s[8:9], 0, v5, s[8:9]
	v_cmp_gt_i64_e32 vcc, s[12:13], v[6:7]
	v_readlane_b32 s13, v3, 41
	s_mov_b32 s12, 22
	v_addc_co_u32_e32 v5, vcc, 0, v5, vcc
	s_cmp_lt_u32 s42, 40
	s_cbranch_scc1 .Lsel_done
	v_cmp_gt_i64_e64 s[8:9], s[10:11], v[6:7]
	v_readlane_b32 s11, v3, 42
	s_mov_b32 s10, 21
	v_addc_co_u32_e64 v5, s[8:9], 0, v5, s[8:9]
	v_cmp_gt_i64_e32 vcc, s[12:13], v[6:7]
	v_readlane_b32 s13, v3, 43
	s_mov_b32 s12, 20
	v_addc_co_u32_e32 v5, vcc, 0, v5, vcc
	v_cmp_gt_i64_e64 s[8:9], s[10:11], v[6:7]
	v_readlane_b32 s11, v3, 44
	s_mov_b32 s10, 19
	v_addc_co_u32_e64 v5, s[8:9], 0, v5, s[8:9]
	v_cmp_gt_i64_e32 vcc, s[12:13], v[6:7]
	v_readlane_b32 s13, v3, 45
	s_mov_b32 s12, 18
	v_addc_co_u32_e32 v5, vcc, 0, v5, vcc
	v_cmp_gt_i64_e64 s[8:9], s[10:11], v[6:7]
	v_readlane_b32 s11, v3, 46
	s_mov_b32 s10, 17
	v_addc_co_u32_e64 v5, s[8:9], 0, v5, s[8:9]
	v_cmp_gt_i64_e32 vcc, s[12:13], v[6:7]
	v_readlane_b32 s13, v3, 47
	s_mov_b32 s12, 16
	v_addc_co_u32_e32 v5, vcc, 0, v5, vcc
	v_cmp_gt_i64_e64 s[8:9], s[10:11], v[6:7]
	v_readlane_b32 s11, v3, 48
	s_mov_b32 s10, 15
	v_addc_co_u32_e64 v5, s[8:9], 0, v5, s[8:9]
	v_cmp_gt_i64_e32 vcc, s[12:13], v[6:7]
	v_readlane_b32 s13, v3, 49
	s_mov_b32 s12, 14
	v_addc_co_u32_e32 v5, vcc, 0, v5, vcc
	s_cmp_lt_u32 s42, 48
	s_cbranch_scc1 .Lsel_done
	v_cmp_gt_i64_e64 s[8:9], s[10:11], v[6:7]
	v_readlane_b32 s11, v3, 50
	s_mov_b32 s10, 13
	v_addc_co_u32_e64 v5, s[8:9], 0, v5, s[8:9]
	v_cmp_gt_i64_e32 vcc, s[12:13], v[6:7]
	v_readlane_b32 s13, v3, 51
	s_mov_b32 s12, 12
	v_addc_co_u32_e32 v5, vcc, 0, v5, vcc
	v_cmp_gt_i64_e64 s[8:9], s[10:11], v[6:7]
	v_readlane_b32 s11, v3, 52
	s_mov_b32 s10, 11
	v_addc_co_u32_e64 v5, s[8:9], 0, v5, s[8:9]
	v_cmp_gt_i64_e32 vcc, s[12:13], v[6:7]
	v_readlane_b32 s13, v3, 53
	s_mov_b32 s12, 10
	v_addc_co_u32_e32 v5, vcc, 0, v5, vcc
	v_cmp_gt_i64_e64 s[8:9], s[10:11], v[6:7]
	v_readlane_b32 s11, v3, 54
	s_mov_b32 s10, 9
	v_addc_co_u32_e64 v5, s[8:9], 0, v5, s[8:9]
	v_cmp_gt_i64_e32 vcc, s[12:13], v[6:7]
	v_readlane_b32 s13, v3, 55
	s_mov_b32 s12, 8
	v_addc_co_u32_e32 v5, vcc, 0, v5, vcc
	v_cmp_gt_i64_e64 s[8:9], s[10:11], v[6:7]
	v_readlane_b32 s11, v3, 56
	s_mov_b32 s10, 7
	v_addc_co_u32_e64 v5, s[8:9], 0, v5, s[8:9]
	v_cmp_gt_i64_e32 vcc, s[12:13], v[6:7]
	v_readlane_b32 s13, v3, 57
	s_mov_b32 s12, 6
	v_addc_co_u32_e32 v5, vcc, 0, v5, vcc
	s_cmp_lt_u32 s42, 56
	s_cbranch_scc1 .Lsel_done
	v_cmp_gt_i64_e64 s[8:9], s[10:11], v[6:7]
	v_readlane_b32 s11, v3, 58
	s_mov_b32 s10, 5
	v_addc_co_u32_e64 v5, s[8:9], 0, v5, s[8:9]
	v_cmp_gt_i64_e32 vcc, s[12:13], v[6:7]
	v_readlane_b32 s13, v3, 59
	s_mov_b32 s12, 4
	v_addc_co_u32_e32 v5, vcc, 0, v5, vcc
	v_cmp_gt_i64_e64 s[8:9], s[10:11], v[6:7]
	v_readlane_b32 s11, v3, 60
	s_mov_b32 s10, 3
	v_addc_co_u32_e64 v5, s[8:9], 0, v5, s[8:9]
	v_cmp_gt_i64_e32 vcc, s[12:13], v[6:7]
	v_readlane_b32 s13, v3, 61
	s_mov_b32 s12, 2
	v_addc_co_u32_e32 v5, vcc, 0, v5, vcc
	v_cmp_gt_i64_e64 s[8:9], s[10:11], v[6:7]
	v_readlane_b32 s11, v3, 62
	s_mov_b32 s10, 1
	v_addc_co_u32_e64 v5, s[8:9], 0, v5, s[8:9]
	v_cmp_gt_i64_e32 vcc, s[12:13], v[6:7]
	v_readlane_b32 s13, v3, 63
	s_mov_b32 s12, 0
	v_addc_co_u32_e32 v5, vcc, 0, v5, vcc
	v_cmp_gt_i64_e64 s[8:9], s[10:11], v[6:7]
	s_nop 1
	v_addc_co_u32_e64 v5, s[8:9], 0, v5, s[8:9]
	v_cmp_gt_i64_e32 vcc, s[12:13], v[6:7]
	s_nop 1
	v_addc_co_u32_e32 v5, vcc, 0, v5, vcc
.Lsel_done:
	s_nop 0
	s_mov_b32 s10, 0xf0c9f2ca
	v_cmp_gt_u32_e64 s[8:9], 16, v5
	v_cmp_lt_f32_e64 s[10:11], s10, v3
	s_and_b64 s[8:9], s[8:9], s[10:11]
	v_cndmask_b32_e64 v3, 0, 1, s[8:9]
	v_cmp_ne_u32_e64 s[10:11], 0, v3
	s_and_saveexec_b64 s[8:9], s[4:5]
	s_cbranch_execz .LBB0_94
	v_lshl_add_u32 v2, v2, 3, v202
	v_mov_b64_e32 v[4:5], s[10:11]
	ds_write_b64 v2, v[4:5]
	s_branch .LBB0_94
